# speedup vs baseline: 1.0080x; 1.0049x over previous
; template <int DQK>
; __device__ __forceinline__ void attn_unit64(LAS char* lds, const bf16x8 (&qa)[DQK / 16], const bf16x8 (&qb)[DQK / 16],
;                                             const bf16_t* Kg, int ldk, const bf16_t* Vg, int ldv, int t0, int t1, bf16_t* Oga, int ogb_off) {
;     ...
;     u32x4 kreg0, kreg1 = (u32x4){0u, 0u, 0u, 0u}, vreg;
;     { const char* Kt = (const char*)(Kg + (size_t)t0 * 64 * ldk); const char* Vt = (const char*)(Vg + (size_t)t0 * 64 * ldv);
;       kreg0 = *(const u32x4*)(Kt + ksrc0); if (k2) kreg1 = *(const u32x4*)(Kt + ksrc1); vreg = *(const u32x4*)(Vt + vsrc); }
;     *(LAS u32x4*)(lds + kdst0) = kreg0; if (k2) *(LAS u32x4*)(lds + kdst1) = kreg1; *(LAS u32x4*)(lds + vdst) = vreg;
;     __syncthreads();
;     int cur = 0;
;     for (int t = t0; t < t1; ++t) {
;         const bool more = (t + 1 < t1);
;         if (more) { const char* Kt = (const char*)(Kg + (size_t)(t + 1) * 64 * ldk); const char* Vt = (const char*)(Vg + (size_t)(t + 1) * 64 * ldv);
;             kreg0 = *(const u32x4*)(Kt + ksrc0); if (k2) kreg1 = *(const u32x4*)(Kt + ksrc1); vreg = *(const u32x4*)(Vt + vsrc); }
;         const LAS char* kb = lds + cur * BUF + kfr; const LAS char* vb = lds + cur * BUF + vfr;
; #pragma nounroll
;         for (int kv = 0; kv < 2; ++kv) {
;             __builtin_amdgcn_iglp_opt(0);
;             f32x16 sa, sb;
; #pragma unroll
;             for (int i = 0; i < 16; ++i) { sa[i] = 0.f; sb[i] = 0.f; }
; #pragma unroll
;             for (int ds = 0; ds < DQK / 16; ++ds) {
;                 const bf16x8 kf = *(const LAS bf16x8*)(kb + kv * 32 * KP + ds * 32);
;                 sa = __builtin_amdgcn_mfma_f32_32x32x16_bf16(kf, qa[ds], sa, 0, 0, 0);
;                 sb = __builtin_amdgcn_mfma_f32_32x32x16_bf16(kf, qb[ds], sb, 0, 0, 0);
;             }
; #pragma unroll
;             for (int i = 0; i < 16; i += 2) { sa[i] = __builtin_amdgcn_exp2f(sa[i]); sa[i + 1] = __builtin_amdgcn_exp2f(sa[i + 1]); la0 += sa[i]; la1 += sa[i + 1];
;                                                sb[i] = __builtin_amdgcn_exp2f(sb[i]); sb[i + 1] = __builtin_amdgcn_exp2f(sb[i + 1]); lb0 += sb[i]; lb1 += sb[i + 1]; }
;             bf16x8 pa[2], pb[2]; pa[0] = pack8(sa, 0); pa[1] = pack8(sa, 1); pb[0] = pack8(sb, 0); pb[1] = pack8(sb, 1);
; #pragma unroll
;             for (int s2 = 0; s2 < 2; ++s2) {
;                 const int s = 2 * kv + s2;
.LBB0_1127:
	v_add_u32_e32 v238, v175, v176
	v_add_u32_e32 v239, v177, v178
	s_mov_b32 s4, 0
	ds_read_b128 v[182:185], v238
	ds_read_b128 v[186:189], v238 offset:32
	ds_read_b128 v[190:193], v238 offset:64
	ds_read_b128 v[194:197], v238 offset:96
	ds_read_b128 v[198:201], v238 offset:128
	ds_read_b128 v[202:205], v238 offset:160
	s_add_u32 s22, s18, 0x3000
	s_addc_u32 s23, s19, 0
	global_load_dwordx4 v[96:99], v160, s[22:23]
	s_cmp_eq_u64 s[0:1], 0
	s_cbranch_scc1 .Lp11_g1_pro
	global_load_dwordx4 v[100:103], v166, s[22:23]
.Lp11_g1_pro:
	s_mov_b32 s24, 0x2000
	s_mov_b32 s25, 0
	v_lshl_add_u64 v[180:181], v[168:169], 0, s[24:25]
	global_load_dwordx4 v[104:107], v[180:181], off
	v_mov_b32_e32 v64, 0xf149f2ca
	v_mov_b32_e32 v65, v64
	v_mov_b32_e32 v66, v64
	v_mov_b32_e32 v67, v64
	v_mov_b32_e32 v68, v64
	v_mov_b32_e32 v69, v64
	v_mov_b32_e32 v70, v64
	v_mov_b32_e32 v71, v64
	v_mov_b32_e32 v72, v64
	v_mov_b32_e32 v73, v64
	v_mov_b32_e32 v74, v64
	v_mov_b32_e32 v75, v64
	v_mov_b32_e32 v76, v64
	v_mov_b32_e32 v77, v64
	v_mov_b32_e32 v78, v64
	v_mov_b32_e32 v79, v64
	v_mov_b32_e32 v214, 0
	v_mov_b32_e32 v215, 0
	v_mov_b32_e32 v216, 0
	v_mov_b32_e32 v217, 0
	v_mov_b32_e32 v218, 0
	v_mov_b32_e32 v219, 0
	v_mov_b32_e32 v220, 0
	v_mov_b32_e32 v221, 0
	v_mov_b32_e32 v248, 0
	v_mov_b32_e32 v249, 0
	v_mov_b32_e32 v250, 0
	v_mov_b32_e32 v251, 0
	v_mov_b32_e32 v252, 0
	v_mov_b32_e32 v253, 0
	v_mov_b32_e32 v254, 0
	v_mov_b32_e32 v255, 0
.Lp11_loop:
	s_waitcnt lgkmcnt(0)
	v_mfma_f32_32x32x16_bf16 v[80:95], v[182:185], v[128:131], 0
	v_exp_f32_e32 v64, v64
	v_exp_f32_e32 v65, v65
	v_exp_f32_e32 v66, v66
	v_exp_f32_e32 v67, v67
	v_mfma_f32_32x32x16_bf16 v[80:95], v[186:189], v[124:127], v[80:95]
	v_exp_f32_e32 v68, v68
	v_exp_f32_e32 v69, v69
	v_cvt_pk_bf16_f32 v230, v64, v65
	v_cvt_pk_bf16_f32 v231, v66, v67
	v_mfma_f32_32x32x16_bf16 v[80:95], v[190:193], v[120:123], v[80:95]
	v_exp_f32_e32 v70, v70
	v_exp_f32_e32 v71, v71
	v_exp_f32_e32 v72, v72
	v_cvt_pk_bf16_f32 v232, v68, v69
	v_mfma_f32_32x32x16_bf16 v[80:95], v[194:197], v[116:119], v[80:95]
	v_exp_f32_e32 v73, v73
	v_exp_f32_e32 v74, v74
	v_cvt_pk_bf16_f32 v233, v70, v71
	v_exp_f32_e32 v75, v75
	v_mfma_f32_32x32x16_bf16 v[80:95], v[198:201], v[108:111], v[80:95]
	v_exp_f32_e32 v76, v76
	v_exp_f32_e32 v77, v77
	v_cvt_pk_bf16_f32 v234, v72, v73
	v_cvt_pk_bf16_f32 v235, v74, v75
	v_mfma_f32_32x32x16_bf16 v[80:95], v[202:205], v[112:115], v[80:95]
	v_exp_f32_e32 v78, v78
	v_exp_f32_e32 v79, v79
	v_cvt_pk_bf16_f32 v236, v76, v77
	v_cvt_pk_bf16_f32 v237, v78, v79
	v_mfma_f32_32x32x16_bf16 v[16:31], v[248:251], v[230:233], v[16:31]
	ds_read_b64_tr_b16 v[248:249], v239 offset:13312
	ds_read_b64_tr_b16 v[250:251], v239 offset:13824
	v_add_f32_e32 v172, v172, v64
	v_add_f32_e32 v173, v173, v65
	v_add_f32_e32 v172, v172, v66
	v_add_f32_e32 v173, v173, v67
	v_mfma_f32_32x32x16_bf16 v[0:15], v[252:255], v[230:233], v[0:15]
	ds_read_b64_tr_b16 v[252:253], v239 offset:17408
	ds_read_b64_tr_b16 v[254:255], v239 offset:17920
	v_add_f32_e32 v172, v172, v68
	v_add_f32_e32 v173, v173, v69
	v_add_f32_e32 v172, v172, v70
	v_add_f32_e32 v173, v173, v71
	v_mfma_f32_32x32x16_bf16 v[16:31], v[214:217], v[234:237], v[16:31]
	ds_read_b64_tr_b16 v[214:215], v239 offset:14336
	ds_read_b64_tr_b16 v[216:217], v239 offset:14848
	v_add_f32_e32 v172, v172, v72
	v_add_f32_e32 v173, v173, v73
	v_add_f32_e32 v172, v172, v74
	v_add_f32_e32 v173, v173, v75
	v_mfma_f32_32x32x16_bf16 v[0:15], v[218:221], v[234:237], v[0:15]
	ds_read_b64_tr_b16 v[218:219], v239 offset:18432
	ds_read_b64_tr_b16 v[220:221], v239 offset:18944
	v_add_f32_e32 v172, v172, v76
	v_add_f32_e32 v173, v173, v77
	v_add_f32_e32 v172, v172, v78
	v_add_f32_e32 v173, v173, v79
	v_mfma_f32_32x32x16_bf16 v[64:79], v[182:185], v[132:135], 0
	ds_read_b128 v[182:185], v238 offset:6656
	v_exp_f32_e32 v80, v80
	v_exp_f32_e32 v81, v81
	v_exp_f32_e32 v82, v82
	v_exp_f32_e32 v83, v83
	v_mfma_f32_32x32x16_bf16 v[64:79], v[186:189], v[136:139], v[64:79]
	ds_read_b128 v[186:189], v238 offset:6688
	v_exp_f32_e32 v84, v84
	v_exp_f32_e32 v85, v85
	v_cvt_pk_bf16_f32 v222, v80, v81
	v_cvt_pk_bf16_f32 v223, v82, v83
	v_mfma_f32_32x32x16_bf16 v[64:79], v[190:193], v[140:143], v[64:79]
	ds_read_b128 v[190:193], v238 offset:6720
	v_exp_f32_e32 v86, v86
	v_exp_f32_e32 v87, v87
	v_exp_f32_e32 v88, v88
	v_cvt_pk_bf16_f32 v224, v84, v85
	v_mfma_f32_32x32x16_bf16 v[64:79], v[194:197], v[144:147], v[64:79]
	ds_read_b128 v[194:197], v238 offset:6752
	v_exp_f32_e32 v89, v89
	v_exp_f32_e32 v90, v90
	v_cvt_pk_bf16_f32 v225, v86, v87
	v_exp_f32_e32 v91, v91
	v_mfma_f32_32x32x16_bf16 v[64:79], v[198:201], v[148:151], v[64:79]
	ds_read_b128 v[198:201], v238 offset:6784
	v_exp_f32_e32 v92, v92
	v_exp_f32_e32 v93, v93
	v_cvt_pk_bf16_f32 v226, v88, v89
	v_cvt_pk_bf16_f32 v227, v90, v91
	v_mfma_f32_32x32x16_bf16 v[64:79], v[202:205], v[152:155], v[64:79]
	ds_read_b128 v[202:205], v238 offset:6816
	v_exp_f32_e32 v94, v94
	v_exp_f32_e32 v95, v95
	v_cvt_pk_bf16_f32 v228, v92, v93
	v_cvt_pk_bf16_f32 v229, v94, v95
	s_waitcnt lgkmcnt(6)
	v_mfma_f32_32x32x16_bf16 v[32:47], v[248:251], v[222:225], v[32:47]
	v_add_f32_e32 v170, v170, v80
	v_add_f32_e32 v171, v171, v81
	v_add_f32_e32 v170, v170, v82
	v_add_f32_e32 v171, v171, v83
	s_waitcnt vmcnt(0)
	ds_write_b128 v159, v[96:99] offset:21504
	s_cmp_eq_u64 s[0:1], 0
	v_mfma_f32_32x32x16_bf16 v[48:63], v[252:255], v[222:225], v[48:63]
	v_add_f32_e32 v170, v170, v84
	v_add_f32_e32 v171, v171, v85
	v_add_f32_e32 v170, v170, v86
	v_add_f32_e32 v171, v171, v87
	s_cbranch_scc1 .Lp11_w1_a0
	ds_write_b128 v212, v[100:103] offset:21504
; template <int DQK>
; __device__ __forceinline__ void attn_unit64(LAS char* lds, const bf16x8 (&qa)[DQK / 16], const bf16x8 (&qb)[DQK / 16],
;                                             const bf16_t* Kg, int ldk, const bf16_t* Vg, int ldv, int t0, int t1, bf16_t* Oga, int ogb_off) {
;     ...
;         if (more) { const char* Kt = (const char*)(Kg + (size_t)(t + 1) * 64 * ldk); const char* Vt = (const char*)(Vg + (size_t)(t + 1) * 64 * ldv);
;             kreg0 = *(const u32x4*)(Kt + ksrc0); if (k2) kreg1 = *(const u32x4*)(Kt + ksrc1); vreg = *(const u32x4*)(Vt + vsrc); }
;         const LAS char* kb = lds + cur * BUF + kfr; const LAS char* vb = lds + cur * BUF + vfr;
; #pragma nounroll
;         for (int kv = 0; kv < 2; ++kv) {
;             __builtin_amdgcn_iglp_opt(0);
;             f32x16 sa, sb;
; #pragma unroll
;             for (int i = 0; i < 16; ++i) { sa[i] = 0.f; sb[i] = 0.f; }
; #pragma unroll
;             for (int ds = 0; ds < DQK / 16; ++ds) {
;                 const bf16x8 kf = *(const LAS bf16x8*)(kb + kv * 32 * KP + ds * 32);
;                 sa = __builtin_amdgcn_mfma_f32_32x32x16_bf16(kf, qa[ds], sa, 0, 0, 0);
;                 sb = __builtin_amdgcn_mfma_f32_32x32x16_bf16(kf, qb[ds], sb, 0, 0, 0);
;             }
; #pragma unroll
;             for (int i = 0; i < 16; i += 2) { sa[i] = __builtin_amdgcn_exp2f(sa[i]); sa[i + 1] = __builtin_amdgcn_exp2f(sa[i + 1]); la0 += sa[i]; la1 += sa[i + 1];
;                                                sb[i] = __builtin_amdgcn_exp2f(sb[i]); sb[i + 1] = __builtin_amdgcn_exp2f(sb[i + 1]); lb0 += sb[i]; lb1 += sb[i + 1]; }
;             bf16x8 pa[2], pb[2]; pa[0] = pack8(sa, 0); pa[1] = pack8(sa, 1); pb[0] = pack8(sb, 0); pb[1] = pack8(sb, 1);
; #pragma unroll
;             for (int s2 = 0; s2 < 2; ++s2) {
;                 const int s = 2 * kv + s2;
;                 const s16x4 a0 = vtr(vb + (16 * s) * 64), a1 = vtr(vb + (16 * s + 8) * 64), c0 = vtr(vb + 4096 + (16 * s) * 64), c1 = vtr(vb + 4096 + (16 * s + 8) * 64);
;                 const bf16x8 va = (bf16x8){a0[0], a0[1], a0[2], a0[3], a1[0], a1[1], a1[2], a1[3]}, vc = (bf16x8){c0[0], c0[1], c0[2], c0[3], c1[0], c1[1], c1[2], c1[3]};
;                 oa0 = __builtin_amdgcn_mfma_f32_32x32x16_bf16(va, pa[s2], oa0, 0, 0, 0);
;                 oa1 = __builtin_amdgcn_mfma_f32_32x32x16_bf16(vc, pa[s2], oa1, 0, 0, 0);
.Lp11_w1_a0:
	ds_write_b128 v179, v[104:107] offset:34816
	v_mfma_f32_32x32x16_bf16 v[32:47], v[214:217], v[226:229], v[32:47]
	v_add_f32_e32 v170, v170, v88
	v_add_f32_e32 v171, v171, v89
	v_add_f32_e32 v170, v170, v90
	v_add_f32_e32 v171, v171, v91
	s_add_u32 s22, s22, 0x3000
	s_addc_u32 s23, s23, 0
	v_lshl_add_u64 v[180:181], v[180:181], 0, s[24:25]
	v_mfma_f32_32x32x16_bf16 v[48:63], v[218:221], v[226:229], v[48:63]
	v_add_f32_e32 v170, v170, v92
	v_add_f32_e32 v171, v171, v93
	v_add_f32_e32 v170, v170, v94
	v_add_f32_e32 v171, v171, v95
	global_load_dwordx4 v[96:99], v160, s[22:23]
	s_cmp_eq_u64 s[0:1], 0
	s_cbranch_scc1 .Lp11_g1_a0
	global_load_dwordx4 v[100:103], v166, s[22:23]
.Lp11_g1_a0:
	global_load_dwordx4 v[104:107], v[180:181], off
	s_waitcnt lgkmcnt(2)
	v_mfma_f32_32x32x16_bf16 v[80:95], v[182:185], v[128:131], 0
	v_exp_f32_e32 v64, v64
	v_exp_f32_e32 v65, v65
	v_exp_f32_e32 v66, v66
	v_exp_f32_e32 v67, v67
	v_mfma_f32_32x32x16_bf16 v[80:95], v[186:189], v[124:127], v[80:95]
	v_exp_f32_e32 v68, v68
	v_exp_f32_e32 v69, v69
	v_cvt_pk_bf16_f32 v230, v64, v65
	v_cvt_pk_bf16_f32 v231, v66, v67
	v_mfma_f32_32x32x16_bf16 v[80:95], v[190:193], v[120:123], v[80:95]
	v_exp_f32_e32 v70, v70
	v_exp_f32_e32 v71, v71
	v_exp_f32_e32 v72, v72
	v_cvt_pk_bf16_f32 v232, v68, v69
	v_mfma_f32_32x32x16_bf16 v[80:95], v[194:197], v[116:119], v[80:95]
	v_exp_f32_e32 v73, v73
	v_exp_f32_e32 v74, v74
	v_cvt_pk_bf16_f32 v233, v70, v71
	v_exp_f32_e32 v75, v75
	v_mfma_f32_32x32x16_bf16 v[80:95], v[198:201], v[108:111], v[80:95]
	v_exp_f32_e32 v76, v76
	v_exp_f32_e32 v77, v77
	v_cvt_pk_bf16_f32 v234, v72, v73
	v_cvt_pk_bf16_f32 v235, v74, v75
	v_mfma_f32_32x32x16_bf16 v[80:95], v[202:205], v[112:115], v[80:95]
	v_exp_f32_e32 v78, v78
	v_exp_f32_e32 v79, v79
	v_cvt_pk_bf16_f32 v236, v76, v77
	v_cvt_pk_bf16_f32 v237, v78, v79
	v_mfma_f32_32x32x16_bf16 v[16:31], v[248:251], v[230:233], v[16:31]
	ds_read_b64_tr_b16 v[248:249], v239 offset:15360
	ds_read_b64_tr_b16 v[250:251], v239 offset:15872
	v_add_f32_e32 v172, v172, v64
	v_add_f32_e32 v173, v173, v65
	v_add_f32_e32 v172, v172, v66
	v_add_f32_e32 v173, v173, v67
	v_mfma_f32_32x32x16_bf16 v[0:15], v[252:255], v[230:233], v[0:15]
	ds_read_b64_tr_b16 v[252:253], v239 offset:19456
	ds_read_b64_tr_b16 v[254:255], v239 offset:19968
	v_add_f32_e32 v172, v172, v68
	v_add_f32_e32 v173, v173, v69
	v_add_f32_e32 v172, v172, v70
	v_add_f32_e32 v173, v173, v71
	v_mfma_f32_32x32x16_bf16 v[16:31], v[214:217], v[234:237], v[16:31]
	ds_read_b64_tr_b16 v[214:215], v239 offset:16384
	ds_read_b64_tr_b16 v[216:217], v239 offset:16896
	v_add_f32_e32 v172, v172, v72
	v_add_f32_e32 v173, v173, v73
	v_add_f32_e32 v172, v172, v74
	v_add_f32_e32 v173, v173, v75
	v_mfma_f32_32x32x16_bf16 v[0:15], v[218:221], v[234:237], v[0:15]
	ds_read_b64_tr_b16 v[218:219], v239 offset:20480
	ds_read_b64_tr_b16 v[220:221], v239 offset:20992
	v_add_f32_e32 v172, v172, v76
	v_add_f32_e32 v173, v173, v77
	v_add_f32_e32 v172, v172, v78
	v_add_f32_e32 v173, v173, v79
	s_waitcnt lgkmcnt(8)
	s_barrier
	v_mfma_f32_32x32x16_bf16 v[64:79], v[182:185], v[132:135], 0
	ds_read_b128 v[182:185], v238 offset:21504
	v_exp_f32_e32 v80, v80
	v_exp_f32_e32 v81, v81
	v_exp_f32_e32 v82, v82
	v_exp_f32_e32 v83, v83
	v_mfma_f32_32x32x16_bf16 v[64:79], v[186:189], v[136:139], v[64:79]
	ds_read_b128 v[186:189], v238 offset:21536
	v_exp_f32_e32 v84, v84
	v_exp_f32_e32 v85, v85
	v_cvt_pk_bf16_f32 v222, v80, v81
	v_cvt_pk_bf16_f32 v223, v82, v83
	v_mfma_f32_32x32x16_bf16 v[64:79], v[190:193], v[140:143], v[64:79]
	ds_read_b128 v[190:193], v238 offset:21568
	v_exp_f32_e32 v86, v86
	v_exp_f32_e32 v87, v87
	v_exp_f32_e32 v88, v88
	v_cvt_pk_bf16_f32 v224, v84, v85
	v_mfma_f32_32x32x16_bf16 v[64:79], v[194:197], v[144:147], v[64:79]
	ds_read_b128 v[194:197], v238 offset:21600
	v_exp_f32_e32 v89, v89
	v_exp_f32_e32 v90, v90
	v_cvt_pk_bf16_f32 v225, v86, v87
	v_exp_f32_e32 v91, v91
	v_mfma_f32_32x32x16_bf16 v[64:79], v[198:201], v[148:151], v[64:79]
	ds_read_b128 v[198:201], v238 offset:21632
	v_exp_f32_e32 v92, v92
	v_exp_f32_e32 v93, v93
	v_cvt_pk_bf16_f32 v226, v88, v89
	v_cvt_pk_bf16_f32 v227, v90, v91
	v_mfma_f32_32x32x16_bf16 v[64:79], v[202:205], v[152:155], v[64:79]
	ds_read_b128 v[202:205], v238 offset:21664
	v_exp_f32_e32 v94, v94
	v_exp_f32_e32 v95, v95
	v_cvt_pk_bf16_f32 v228, v92, v93
	v_cvt_pk_bf16_f32 v229, v94, v95
	s_waitcnt lgkmcnt(6)
	v_mfma_f32_32x32x16_bf16 v[32:47], v[248:251], v[222:225], v[32:47]
	v_add_f32_e32 v170, v170, v80
	v_add_f32_e32 v171, v171, v81
	v_add_f32_e32 v170, v170, v82
	v_add_f32_e32 v171, v171, v83
	v_mfma_f32_32x32x16_bf16 v[48:63], v[252:255], v[222:225], v[48:63]
	v_add_f32_e32 v170, v170, v84
	v_add_f32_e32 v171, v171, v85
	v_add_f32_e32 v170, v170, v86
	v_add_f32_e32 v171, v171, v87
	v_mfma_f32_32x32x16_bf16 v[32:47], v[214:217], v[226:229], v[32:47]
	v_add_f32_e32 v170, v170, v88
	v_add_f32_e32 v171, v171, v89
	v_add_f32_e32 v170, v170, v90
	v_add_f32_e32 v171, v171, v91
	v_mfma_f32_32x32x16_bf16 v[48:63], v[218:221], v[226:229], v[48:63]
	v_add_f32_e32 v170, v170, v92
	v_add_f32_e32 v171, v171, v93
	v_add_f32_e32 v170, v170, v94
	v_add_f32_e32 v171, v171, v95
	s_add_i32 s4, s4, 1
	s_cmp_lt_u32 s4, s39
	s_cbranch_scc0 .Lp11_drain
; template <int DQK>
; __device__ __forceinline__ void attn_unit64(LAS char* lds, const bf16x8 (&qa)[DQK / 16], const bf16x8 (&qb)[DQK / 16],
;                                             const bf16_t* Kg, int ldk, const bf16_t* Vg, int ldv, int t0, int t1, bf16_t* Oga, int ogb_off) {
;     ...
;         for (int kv = 0; kv < 2; ++kv) {
;             __builtin_amdgcn_iglp_opt(0);
;             f32x16 sa, sb;
; #pragma unroll
;             for (int i = 0; i < 16; ++i) { sa[i] = 0.f; sb[i] = 0.f; }
; #pragma unroll
;             for (int ds = 0; ds < DQK / 16; ++ds) {
;                 const bf16x8 kf = *(const LAS bf16x8*)(kb + kv * 32 * KP + ds * 32);
;                 sa = __builtin_amdgcn_mfma_f32_32x32x16_bf16(kf, qa[ds], sa, 0, 0, 0);
;                 sb = __builtin_amdgcn_mfma_f32_32x32x16_bf16(kf, qb[ds], sb, 0, 0, 0);
;             }
; #pragma unroll
;             for (int i = 0; i < 16; i += 2) { sa[i] = __builtin_amdgcn_exp2f(sa[i]); sa[i + 1] = __builtin_amdgcn_exp2f(sa[i + 1]); la0 += sa[i]; la1 += sa[i + 1];
;                                                sb[i] = __builtin_amdgcn_exp2f(sb[i]); sb[i + 1] = __builtin_amdgcn_exp2f(sb[i + 1]); lb0 += sb[i]; lb1 += sb[i + 1]; }
;             bf16x8 pa[2], pb[2]; pa[0] = pack8(sa, 0); pa[1] = pack8(sa, 1); pb[0] = pack8(sb, 0); pb[1] = pack8(sb, 1);
; #pragma unroll
;             for (int s2 = 0; s2 < 2; ++s2) {
;                 const int s = 2 * kv + s2;
;                 const s16x4 a0 = vtr(vb + (16 * s) * 64), a1 = vtr(vb + (16 * s + 8) * 64), c0 = vtr(vb + 4096 + (16 * s) * 64), c1 = vtr(vb + 4096 + (16 * s + 8) * 64);
;                 const bf16x8 va = (bf16x8){a0[0], a0[1], a0[2], a0[3], a1[0], a1[1], a1[2], a1[3]}, vc = (bf16x8){c0[0], c0[1], c0[2], c0[3], c1[0], c1[1], c1[2], c1[3]};
;                 oa0 = __builtin_amdgcn_mfma_f32_32x32x16_bf16(va, pa[s2], oa0, 0, 0, 0);
;                 oa1 = __builtin_amdgcn_mfma_f32_32x32x16_bf16(vc, pa[s2], oa1, 0, 0, 0);
;                 ob0 = __builtin_amdgcn_mfma_f32_32x32x16_bf16(va, pb[s2], ob0, 0, 0, 0);
;                 ob1 = __builtin_amdgcn_mfma_f32_32x32x16_bf16(vc, pb[s2], ob1, 0, 0, 0);
;             }
;         }
;         if (more) { const unsigned bo = (cur ^ 1) * BUF; *(LAS u32x4*)(lds + bo + kdst0) = kreg0; if (k2) *(LAS u32x4*)(lds + bo + kdst1) = kreg1; *(LAS u32x4*)(lds + bo + vdst) = vreg; }
	s_waitcnt lgkmcnt(0)
	v_mfma_f32_32x32x16_bf16 v[80:95], v[182:185], v[128:131], 0
	v_exp_f32_e32 v64, v64
	v_exp_f32_e32 v65, v65
	v_exp_f32_e32 v66, v66
	v_exp_f32_e32 v67, v67
	v_mfma_f32_32x32x16_bf16 v[80:95], v[186:189], v[124:127], v[80:95]
	v_exp_f32_e32 v68, v68
	v_exp_f32_e32 v69, v69
	v_cvt_pk_bf16_f32 v230, v64, v65
	v_cvt_pk_bf16_f32 v231, v66, v67
	v_mfma_f32_32x32x16_bf16 v[80:95], v[190:193], v[120:123], v[80:95]
	v_exp_f32_e32 v70, v70
	v_exp_f32_e32 v71, v71
	v_exp_f32_e32 v72, v72
	v_cvt_pk_bf16_f32 v232, v68, v69
	v_mfma_f32_32x32x16_bf16 v[80:95], v[194:197], v[116:119], v[80:95]
	v_exp_f32_e32 v73, v73
	v_exp_f32_e32 v74, v74
	v_cvt_pk_bf16_f32 v233, v70, v71
	v_exp_f32_e32 v75, v75
	v_mfma_f32_32x32x16_bf16 v[80:95], v[198:201], v[108:111], v[80:95]
	v_exp_f32_e32 v76, v76
	v_exp_f32_e32 v77, v77
	v_cvt_pk_bf16_f32 v234, v72, v73
	v_cvt_pk_bf16_f32 v235, v74, v75
	v_mfma_f32_32x32x16_bf16 v[80:95], v[202:205], v[112:115], v[80:95]
	v_exp_f32_e32 v78, v78
	v_exp_f32_e32 v79, v79
	v_cvt_pk_bf16_f32 v236, v76, v77
	v_cvt_pk_bf16_f32 v237, v78, v79
	v_mfma_f32_32x32x16_bf16 v[16:31], v[248:251], v[230:233], v[16:31]
	ds_read_b64_tr_b16 v[248:249], v239 offset:34816
	ds_read_b64_tr_b16 v[250:251], v239 offset:35328
	v_add_f32_e32 v172, v172, v64
	v_add_f32_e32 v173, v173, v65
	v_add_f32_e32 v172, v172, v66
	v_add_f32_e32 v173, v173, v67
	v_mfma_f32_32x32x16_bf16 v[0:15], v[252:255], v[230:233], v[0:15]
	ds_read_b64_tr_b16 v[252:253], v239 offset:38912
	ds_read_b64_tr_b16 v[254:255], v239 offset:39424
	v_add_f32_e32 v172, v172, v68
	v_add_f32_e32 v173, v173, v69
	v_add_f32_e32 v172, v172, v70
	v_add_f32_e32 v173, v173, v71
	v_mfma_f32_32x32x16_bf16 v[16:31], v[214:217], v[234:237], v[16:31]
	ds_read_b64_tr_b16 v[214:215], v239 offset:35840
	ds_read_b64_tr_b16 v[216:217], v239 offset:36352
	v_add_f32_e32 v172, v172, v72
	v_add_f32_e32 v173, v173, v73
	v_add_f32_e32 v172, v172, v74
	v_add_f32_e32 v173, v173, v75
	v_mfma_f32_32x32x16_bf16 v[0:15], v[218:221], v[234:237], v[0:15]
	ds_read_b64_tr_b16 v[218:219], v239 offset:39936
	ds_read_b64_tr_b16 v[220:221], v239 offset:40448
	v_add_f32_e32 v172, v172, v76
	v_add_f32_e32 v173, v173, v77
	v_add_f32_e32 v172, v172, v78
	v_add_f32_e32 v173, v173, v79
	v_mfma_f32_32x32x16_bf16 v[64:79], v[182:185], v[132:135], 0
	ds_read_b128 v[182:185], v238 offset:28160
	v_exp_f32_e32 v80, v80
	v_exp_f32_e32 v81, v81
	v_exp_f32_e32 v82, v82
	v_exp_f32_e32 v83, v83
	v_mfma_f32_32x32x16_bf16 v[64:79], v[186:189], v[136:139], v[64:79]
	ds_read_b128 v[186:189], v238 offset:28192
	v_exp_f32_e32 v84, v84
	v_exp_f32_e32 v85, v85
	v_cvt_pk_bf16_f32 v222, v80, v81
	v_cvt_pk_bf16_f32 v223, v82, v83
	v_mfma_f32_32x32x16_bf16 v[64:79], v[190:193], v[140:143], v[64:79]
	ds_read_b128 v[190:193], v238 offset:28224
	v_exp_f32_e32 v86, v86
	v_exp_f32_e32 v87, v87
	v_exp_f32_e32 v88, v88
	v_cvt_pk_bf16_f32 v224, v84, v85
	v_mfma_f32_32x32x16_bf16 v[64:79], v[194:197], v[144:147], v[64:79]
	ds_read_b128 v[194:197], v238 offset:28256
	v_exp_f32_e32 v89, v89
	v_exp_f32_e32 v90, v90
	v_cvt_pk_bf16_f32 v225, v86, v87
	v_exp_f32_e32 v91, v91
	v_mfma_f32_32x32x16_bf16 v[64:79], v[198:201], v[148:151], v[64:79]
	ds_read_b128 v[198:201], v238 offset:28288
	v_exp_f32_e32 v92, v92
	v_exp_f32_e32 v93, v93
	v_cvt_pk_bf16_f32 v226, v88, v89
	v_cvt_pk_bf16_f32 v227, v90, v91
	v_mfma_f32_32x32x16_bf16 v[64:79], v[202:205], v[152:155], v[64:79]
	ds_read_b128 v[202:205], v238 offset:28320
	v_exp_f32_e32 v94, v94
	v_exp_f32_e32 v95, v95
	v_cvt_pk_bf16_f32 v228, v92, v93
	v_cvt_pk_bf16_f32 v229, v94, v95
	s_waitcnt lgkmcnt(6)
	v_mfma_f32_32x32x16_bf16 v[32:47], v[248:251], v[222:225], v[32:47]
	v_add_f32_e32 v170, v170, v80
	v_add_f32_e32 v171, v171, v81
	v_add_f32_e32 v170, v170, v82
	v_add_f32_e32 v171, v171, v83
	s_waitcnt vmcnt(0)
	ds_write_b128 v159, v[96:99] offset:43008
	s_cmp_eq_u64 s[0:1], 0
	v_mfma_f32_32x32x16_bf16 v[48:63], v[252:255], v[222:225], v[48:63]
	v_add_f32_e32 v170, v170, v84
	v_add_f32_e32 v171, v171, v85
	v_add_f32_e32 v170, v170, v86
	v_add_f32_e32 v171, v171, v87
	s_cbranch_scc1 .Lp11_w1_a1
	ds_write_b128 v212, v[100:103] offset:43008
.Lp11_w1_a1:
	ds_write_b128 v179, v[104:107] offset:56320
	v_mfma_f32_32x32x16_bf16 v[32:47], v[214:217], v[226:229], v[32:47]
	v_add_f32_e32 v170, v170, v88
	v_add_f32_e32 v171, v171, v89
	v_add_f32_e32 v170, v170, v90
	v_add_f32_e32 v171, v171, v91
	s_add_u32 s22, s22, 0x3000
	s_addc_u32 s23, s23, 0
	v_lshl_add_u64 v[180:181], v[180:181], 0, s[24:25]
	v_mfma_f32_32x32x16_bf16 v[48:63], v[218:221], v[226:229], v[48:63]
	v_add_f32_e32 v170, v170, v92
	v_add_f32_e32 v171, v171, v93
	v_add_f32_e32 v170, v170, v94
	v_add_f32_e32 v171, v171, v95
	global_load_dwordx4 v[96:99], v160, s[22:23]
	s_cmp_eq_u64 s[0:1], 0
	s_cbranch_scc1 .Lp11_g1_a1
	global_load_dwordx4 v[100:103], v166, s[22:23]
; template <int DQK>
; __device__ __forceinline__ void attn_unit64(LAS char* lds, const bf16x8 (&qa)[DQK / 16], const bf16x8 (&qb)[DQK / 16],
;                                             const bf16_t* Kg, int ldk, const bf16_t* Vg, int ldv, int t0, int t1, bf16_t* Oga, int ogb_off) {
;     ...
;         for (int kv = 0; kv < 2; ++kv) {
;             __builtin_amdgcn_iglp_opt(0);
;             f32x16 sa, sb;
; #pragma unroll
;             for (int i = 0; i < 16; ++i) { sa[i] = 0.f; sb[i] = 0.f; }
; #pragma unroll
;             for (int ds = 0; ds < DQK / 16; ++ds) {
;                 const bf16x8 kf = *(const LAS bf16x8*)(kb + kv * 32 * KP + ds * 32);
;                 sa = __builtin_amdgcn_mfma_f32_32x32x16_bf16(kf, qa[ds], sa, 0, 0, 0);
;                 sb = __builtin_amdgcn_mfma_f32_32x32x16_bf16(kf, qb[ds], sb, 0, 0, 0);
;             }
; #pragma unroll
;             for (int i = 0; i < 16; i += 2) { sa[i] = __builtin_amdgcn_exp2f(sa[i]); sa[i + 1] = __builtin_amdgcn_exp2f(sa[i + 1]); la0 += sa[i]; la1 += sa[i + 1];
;                                                sb[i] = __builtin_amdgcn_exp2f(sb[i]); sb[i + 1] = __builtin_amdgcn_exp2f(sb[i + 1]); lb0 += sb[i]; lb1 += sb[i + 1]; }
;             bf16x8 pa[2], pb[2]; pa[0] = pack8(sa, 0); pa[1] = pack8(sa, 1); pb[0] = pack8(sb, 0); pb[1] = pack8(sb, 1);
; #pragma unroll
;             for (int s2 = 0; s2 < 2; ++s2) {
;                 const int s = 2 * kv + s2;
;                 const s16x4 a0 = vtr(vb + (16 * s) * 64), a1 = vtr(vb + (16 * s + 8) * 64), c0 = vtr(vb + 4096 + (16 * s) * 64), c1 = vtr(vb + 4096 + (16 * s + 8) * 64);
;                 const bf16x8 va = (bf16x8){a0[0], a0[1], a0[2], a0[3], a1[0], a1[1], a1[2], a1[3]}, vc = (bf16x8){c0[0], c0[1], c0[2], c0[3], c1[0], c1[1], c1[2], c1[3]};
;                 oa0 = __builtin_amdgcn_mfma_f32_32x32x16_bf16(va, pa[s2], oa0, 0, 0, 0);
;                 oa1 = __builtin_amdgcn_mfma_f32_32x32x16_bf16(vc, pa[s2], oa1, 0, 0, 0);
;                 ob0 = __builtin_amdgcn_mfma_f32_32x32x16_bf16(va, pb[s2], ob0, 0, 0, 0);
;                 ob1 = __builtin_amdgcn_mfma_f32_32x32x16_bf16(vc, pb[s2], ob1, 0, 0, 0);
;             }
;         }
;         if (more) { const unsigned bo = (cur ^ 1) * BUF; *(LAS u32x4*)(lds + bo + kdst0) = kreg0; if (k2) *(LAS u32x4*)(lds + bo + kdst1) = kreg1; *(LAS u32x4*)(lds + bo + vdst) = vreg; }
;         __syncthreads();
.Lp11_g1_a1:
	global_load_dwordx4 v[104:107], v[180:181], off
	s_waitcnt lgkmcnt(2)
	v_mfma_f32_32x32x16_bf16 v[80:95], v[182:185], v[128:131], 0
	v_exp_f32_e32 v64, v64
	v_exp_f32_e32 v65, v65
	v_exp_f32_e32 v66, v66
	v_exp_f32_e32 v67, v67
	v_mfma_f32_32x32x16_bf16 v[80:95], v[186:189], v[124:127], v[80:95]
	v_exp_f32_e32 v68, v68
	v_exp_f32_e32 v69, v69
	v_cvt_pk_bf16_f32 v230, v64, v65
	v_cvt_pk_bf16_f32 v231, v66, v67
	v_mfma_f32_32x32x16_bf16 v[80:95], v[190:193], v[120:123], v[80:95]
	v_exp_f32_e32 v70, v70
	v_exp_f32_e32 v71, v71
	v_exp_f32_e32 v72, v72
	v_cvt_pk_bf16_f32 v232, v68, v69
	v_mfma_f32_32x32x16_bf16 v[80:95], v[194:197], v[116:119], v[80:95]
	v_exp_f32_e32 v73, v73
	v_exp_f32_e32 v74, v74
	v_cvt_pk_bf16_f32 v233, v70, v71
	v_exp_f32_e32 v75, v75
	v_mfma_f32_32x32x16_bf16 v[80:95], v[198:201], v[108:111], v[80:95]
	v_exp_f32_e32 v76, v76
	v_exp_f32_e32 v77, v77
	v_cvt_pk_bf16_f32 v234, v72, v73
	v_cvt_pk_bf16_f32 v235, v74, v75
	v_mfma_f32_32x32x16_bf16 v[80:95], v[202:205], v[112:115], v[80:95]
	v_exp_f32_e32 v78, v78
	v_exp_f32_e32 v79, v79
	v_cvt_pk_bf16_f32 v236, v76, v77
	v_cvt_pk_bf16_f32 v237, v78, v79
	v_mfma_f32_32x32x16_bf16 v[16:31], v[248:251], v[230:233], v[16:31]
	ds_read_b64_tr_b16 v[248:249], v239 offset:36864
	ds_read_b64_tr_b16 v[250:251], v239 offset:37376
	v_add_f32_e32 v172, v172, v64
	v_add_f32_e32 v173, v173, v65
	v_add_f32_e32 v172, v172, v66
	v_add_f32_e32 v173, v173, v67
	v_mfma_f32_32x32x16_bf16 v[0:15], v[252:255], v[230:233], v[0:15]
	ds_read_b64_tr_b16 v[252:253], v239 offset:40960
	ds_read_b64_tr_b16 v[254:255], v239 offset:41472
	v_add_f32_e32 v172, v172, v68
	v_add_f32_e32 v173, v173, v69
	v_add_f32_e32 v172, v172, v70
	v_add_f32_e32 v173, v173, v71
	v_mfma_f32_32x32x16_bf16 v[16:31], v[214:217], v[234:237], v[16:31]
	ds_read_b64_tr_b16 v[214:215], v239 offset:37888
	ds_read_b64_tr_b16 v[216:217], v239 offset:38400
	v_add_f32_e32 v172, v172, v72
	v_add_f32_e32 v173, v173, v73
	v_add_f32_e32 v172, v172, v74
	v_add_f32_e32 v173, v173, v75
	v_mfma_f32_32x32x16_bf16 v[0:15], v[218:221], v[234:237], v[0:15]
	ds_read_b64_tr_b16 v[218:219], v239 offset:41984
	ds_read_b64_tr_b16 v[220:221], v239 offset:42496
	v_add_f32_e32 v172, v172, v76
	v_add_f32_e32 v173, v173, v77
	v_add_f32_e32 v172, v172, v78
	v_add_f32_e32 v173, v173, v79
	s_waitcnt lgkmcnt(8)
	s_barrier
	v_mfma_f32_32x32x16_bf16 v[64:79], v[182:185], v[132:135], 0
	ds_read_b128 v[182:185], v238 offset:43008
	v_exp_f32_e32 v80, v80
	v_exp_f32_e32 v81, v81
	v_exp_f32_e32 v82, v82
	v_exp_f32_e32 v83, v83
	v_mfma_f32_32x32x16_bf16 v[64:79], v[186:189], v[136:139], v[64:79]
	ds_read_b128 v[186:189], v238 offset:43040
	v_exp_f32_e32 v84, v84
	v_exp_f32_e32 v85, v85
	v_cvt_pk_bf16_f32 v222, v80, v81
	v_cvt_pk_bf16_f32 v223, v82, v83
	v_mfma_f32_32x32x16_bf16 v[64:79], v[190:193], v[140:143], v[64:79]
	ds_read_b128 v[190:193], v238 offset:43072
	v_exp_f32_e32 v86, v86
	v_exp_f32_e32 v87, v87
	v_exp_f32_e32 v88, v88
	v_cvt_pk_bf16_f32 v224, v84, v85
	v_mfma_f32_32x32x16_bf16 v[64:79], v[194:197], v[144:147], v[64:79]
	ds_read_b128 v[194:197], v238 offset:43104
	v_exp_f32_e32 v89, v89
	v_exp_f32_e32 v90, v90
	v_cvt_pk_bf16_f32 v225, v86, v87
	v_exp_f32_e32 v91, v91
	v_mfma_f32_32x32x16_bf16 v[64:79], v[198:201], v[148:151], v[64:79]
	ds_read_b128 v[198:201], v238 offset:43136
	v_exp_f32_e32 v92, v92
	v_exp_f32_e32 v93, v93
	v_cvt_pk_bf16_f32 v226, v88, v89
	v_cvt_pk_bf16_f32 v227, v90, v91
	v_mfma_f32_32x32x16_bf16 v[64:79], v[202:205], v[152:155], v[64:79]
	ds_read_b128 v[202:205], v238 offset:43168
	v_exp_f32_e32 v94, v94
	v_exp_f32_e32 v95, v95
	v_cvt_pk_bf16_f32 v228, v92, v93
	v_cvt_pk_bf16_f32 v229, v94, v95
	s_waitcnt lgkmcnt(6)
	v_mfma_f32_32x32x16_bf16 v[32:47], v[248:251], v[222:225], v[32:47]
	v_add_f32_e32 v170, v170, v80
	v_add_f32_e32 v171, v171, v81
	v_add_f32_e32 v170, v170, v82
	v_add_f32_e32 v171, v171, v83
	v_mfma_f32_32x32x16_bf16 v[48:63], v[252:255], v[222:225], v[48:63]
	v_add_f32_e32 v170, v170, v84
	v_add_f32_e32 v171, v171, v85
	v_add_f32_e32 v170, v170, v86
	v_add_f32_e32 v171, v171, v87
	v_mfma_f32_32x32x16_bf16 v[32:47], v[214:217], v[226:229], v[32:47]
	v_add_f32_e32 v170, v170, v88
	v_add_f32_e32 v171, v171, v89
	v_add_f32_e32 v170, v170, v90
	v_add_f32_e32 v171, v171, v91
	v_mfma_f32_32x32x16_bf16 v[48:63], v[218:221], v[226:229], v[48:63]
	v_add_f32_e32 v170, v170, v92
	v_add_f32_e32 v171, v171, v93
	v_add_f32_e32 v170, v170, v94
	v_add_f32_e32 v171, v171, v95
	s_add_i32 s4, s4, 1
	s_cmp_lt_u32 s4, s39
	s_cbranch_scc0 .Lp11_drain
; template <int DQK>
; __device__ __forceinline__ void attn_unit64(LAS char* lds, const bf16x8 (&qa)[DQK / 16], const bf16x8 (&qb)[DQK / 16],
;                                             const bf16_t* Kg, int ldk, const bf16_t* Vg, int ldv, int t0, int t1, bf16_t* Oga, int ogb_off) {
;     ...
;         for (int kv = 0; kv < 2; ++kv) {
;             __builtin_amdgcn_iglp_opt(0);
;             f32x16 sa, sb;
; #pragma unroll
;             for (int i = 0; i < 16; ++i) { sa[i] = 0.f; sb[i] = 0.f; }
; #pragma unroll
;             for (int ds = 0; ds < DQK / 16; ++ds) {
;                 const bf16x8 kf = *(const LAS bf16x8*)(kb + kv * 32 * KP + ds * 32);
;                 sa = __builtin_amdgcn_mfma_f32_32x32x16_bf16(kf, qa[ds], sa, 0, 0, 0);
;                 sb = __builtin_amdgcn_mfma_f32_32x32x16_bf16(kf, qb[ds], sb, 0, 0, 0);
;             }
; #pragma unroll
;             for (int i = 0; i < 16; i += 2) { sa[i] = __builtin_amdgcn_exp2f(sa[i]); sa[i + 1] = __builtin_amdgcn_exp2f(sa[i + 1]); la0 += sa[i]; la1 += sa[i + 1];
;                                                sb[i] = __builtin_amdgcn_exp2f(sb[i]); sb[i + 1] = __builtin_amdgcn_exp2f(sb[i + 1]); lb0 += sb[i]; lb1 += sb[i + 1]; }
;             bf16x8 pa[2], pb[2]; pa[0] = pack8(sa, 0); pa[1] = pack8(sa, 1); pb[0] = pack8(sb, 0); pb[1] = pack8(sb, 1);
; #pragma unroll
;             for (int s2 = 0; s2 < 2; ++s2) {
;                 const int s = 2 * kv + s2;
;                 const s16x4 a0 = vtr(vb + (16 * s) * 64), a1 = vtr(vb + (16 * s + 8) * 64), c0 = vtr(vb + 4096 + (16 * s) * 64), c1 = vtr(vb + 4096 + (16 * s + 8) * 64);
;                 const bf16x8 va = (bf16x8){a0[0], a0[1], a0[2], a0[3], a1[0], a1[1], a1[2], a1[3]}, vc = (bf16x8){c0[0], c0[1], c0[2], c0[3], c1[0], c1[1], c1[2], c1[3]};
;                 oa0 = __builtin_amdgcn_mfma_f32_32x32x16_bf16(va, pa[s2], oa0, 0, 0, 0);
;                 oa1 = __builtin_amdgcn_mfma_f32_32x32x16_bf16(vc, pa[s2], oa1, 0, 0, 0);
;                 ob0 = __builtin_amdgcn_mfma_f32_32x32x16_bf16(va, pb[s2], ob0, 0, 0, 0);
;                 ob1 = __builtin_amdgcn_mfma_f32_32x32x16_bf16(vc, pb[s2], ob1, 0, 0, 0);
;             }
;         }
;         if (more) { const unsigned bo = (cur ^ 1) * BUF; *(LAS u32x4*)(lds + bo + kdst0) = kreg0; if (k2) *(LAS u32x4*)(lds + bo + kdst1) = kreg1; *(LAS u32x4*)(lds + bo + vdst) = vreg; }
	s_waitcnt lgkmcnt(0)
	v_mfma_f32_32x32x16_bf16 v[80:95], v[182:185], v[128:131], 0
	v_exp_f32_e32 v64, v64
	v_exp_f32_e32 v65, v65
	v_exp_f32_e32 v66, v66
	v_exp_f32_e32 v67, v67
	v_mfma_f32_32x32x16_bf16 v[80:95], v[186:189], v[124:127], v[80:95]
	v_exp_f32_e32 v68, v68
	v_exp_f32_e32 v69, v69
	v_cvt_pk_bf16_f32 v230, v64, v65
	v_cvt_pk_bf16_f32 v231, v66, v67
	v_mfma_f32_32x32x16_bf16 v[80:95], v[190:193], v[120:123], v[80:95]
	v_exp_f32_e32 v70, v70
	v_exp_f32_e32 v71, v71
	v_exp_f32_e32 v72, v72
	v_cvt_pk_bf16_f32 v232, v68, v69
	v_mfma_f32_32x32x16_bf16 v[80:95], v[194:197], v[116:119], v[80:95]
	v_exp_f32_e32 v73, v73
	v_exp_f32_e32 v74, v74
	v_cvt_pk_bf16_f32 v233, v70, v71
	v_exp_f32_e32 v75, v75
	v_mfma_f32_32x32x16_bf16 v[80:95], v[198:201], v[108:111], v[80:95]
	v_exp_f32_e32 v76, v76
	v_exp_f32_e32 v77, v77
	v_cvt_pk_bf16_f32 v234, v72, v73
	v_cvt_pk_bf16_f32 v235, v74, v75
	v_mfma_f32_32x32x16_bf16 v[80:95], v[202:205], v[112:115], v[80:95]
	v_exp_f32_e32 v78, v78
	v_exp_f32_e32 v79, v79
	v_cvt_pk_bf16_f32 v236, v76, v77
	v_cvt_pk_bf16_f32 v237, v78, v79
	v_mfma_f32_32x32x16_bf16 v[16:31], v[248:251], v[230:233], v[16:31]
	ds_read_b64_tr_b16 v[248:249], v239 offset:56320
	ds_read_b64_tr_b16 v[250:251], v239 offset:56832
	v_add_f32_e32 v172, v172, v64
	v_add_f32_e32 v173, v173, v65
	v_add_f32_e32 v172, v172, v66
	v_add_f32_e32 v173, v173, v67
	v_mfma_f32_32x32x16_bf16 v[0:15], v[252:255], v[230:233], v[0:15]
	ds_read_b64_tr_b16 v[252:253], v239 offset:60416
	ds_read_b64_tr_b16 v[254:255], v239 offset:60928
	v_add_f32_e32 v172, v172, v68
	v_add_f32_e32 v173, v173, v69
	v_add_f32_e32 v172, v172, v70
	v_add_f32_e32 v173, v173, v71
	v_mfma_f32_32x32x16_bf16 v[16:31], v[214:217], v[234:237], v[16:31]
	ds_read_b64_tr_b16 v[214:215], v239 offset:57344
	ds_read_b64_tr_b16 v[216:217], v239 offset:57856
	v_add_f32_e32 v172, v172, v72
	v_add_f32_e32 v173, v173, v73
	v_add_f32_e32 v172, v172, v74
	v_add_f32_e32 v173, v173, v75
	v_mfma_f32_32x32x16_bf16 v[0:15], v[218:221], v[234:237], v[0:15]
	ds_read_b64_tr_b16 v[218:219], v239 offset:61440
	ds_read_b64_tr_b16 v[220:221], v239 offset:61952
	v_add_f32_e32 v172, v172, v76
	v_add_f32_e32 v173, v173, v77
	v_add_f32_e32 v172, v172, v78
	v_add_f32_e32 v173, v173, v79
	v_mfma_f32_32x32x16_bf16 v[64:79], v[182:185], v[132:135], 0
	ds_read_b128 v[182:185], v238 offset:49664
	v_exp_f32_e32 v80, v80
	v_exp_f32_e32 v81, v81
	v_exp_f32_e32 v82, v82
	v_exp_f32_e32 v83, v83
	v_mfma_f32_32x32x16_bf16 v[64:79], v[186:189], v[136:139], v[64:79]
	ds_read_b128 v[186:189], v238 offset:49696
	v_exp_f32_e32 v84, v84
	v_exp_f32_e32 v85, v85
	v_cvt_pk_bf16_f32 v222, v80, v81
	v_cvt_pk_bf16_f32 v223, v82, v83
	v_mfma_f32_32x32x16_bf16 v[64:79], v[190:193], v[140:143], v[64:79]
	ds_read_b128 v[190:193], v238 offset:49728
	v_exp_f32_e32 v86, v86
	v_exp_f32_e32 v87, v87
	v_exp_f32_e32 v88, v88
	v_cvt_pk_bf16_f32 v224, v84, v85
	v_mfma_f32_32x32x16_bf16 v[64:79], v[194:197], v[144:147], v[64:79]
	ds_read_b128 v[194:197], v238 offset:49760
	v_exp_f32_e32 v89, v89
	v_exp_f32_e32 v90, v90
	v_cvt_pk_bf16_f32 v225, v86, v87
	v_exp_f32_e32 v91, v91
	v_mfma_f32_32x32x16_bf16 v[64:79], v[198:201], v[148:151], v[64:79]
	ds_read_b128 v[198:201], v238 offset:49792
	v_exp_f32_e32 v92, v92
	v_exp_f32_e32 v93, v93
	v_cvt_pk_bf16_f32 v226, v88, v89
	v_cvt_pk_bf16_f32 v227, v90, v91
	v_mfma_f32_32x32x16_bf16 v[64:79], v[202:205], v[152:155], v[64:79]
	ds_read_b128 v[202:205], v238 offset:49824
	v_exp_f32_e32 v94, v94
	v_exp_f32_e32 v95, v95
	v_cvt_pk_bf16_f32 v228, v92, v93
	v_cvt_pk_bf16_f32 v229, v94, v95
	s_waitcnt lgkmcnt(6)
	v_mfma_f32_32x32x16_bf16 v[32:47], v[248:251], v[222:225], v[32:47]
	v_add_f32_e32 v170, v170, v80
	v_add_f32_e32 v171, v171, v81
	v_add_f32_e32 v170, v170, v82
	v_add_f32_e32 v171, v171, v83
	s_waitcnt vmcnt(0)
	ds_write_b128 v159, v[96:99] offset:0
	s_cmp_eq_u64 s[0:1], 0
	v_mfma_f32_32x32x16_bf16 v[48:63], v[252:255], v[222:225], v[48:63]
	v_add_f32_e32 v170, v170, v84
	v_add_f32_e32 v171, v171, v85
	v_add_f32_e32 v170, v170, v86
	v_add_f32_e32 v171, v171, v87
	s_cbranch_scc1 .Lp11_w1_a2
	ds_write_b128 v212, v[100:103] offset:0
.Lp11_w1_a2:
	ds_write_b128 v179, v[104:107] offset:13312
	v_mfma_f32_32x32x16_bf16 v[32:47], v[214:217], v[226:229], v[32:47]
	v_add_f32_e32 v170, v170, v88
	v_add_f32_e32 v171, v171, v89
	v_add_f32_e32 v170, v170, v90
	v_add_f32_e32 v171, v171, v91
	s_add_u32 s22, s22, 0x3000
	s_addc_u32 s23, s23, 0
	v_lshl_add_u64 v[180:181], v[180:181], 0, s[24:25]
	v_mfma_f32_32x32x16_bf16 v[48:63], v[218:221], v[226:229], v[48:63]
	v_add_f32_e32 v170, v170, v92
	v_add_f32_e32 v171, v171, v93
	v_add_f32_e32 v170, v170, v94
	v_add_f32_e32 v171, v171, v95
	global_load_dwordx4 v[96:99], v160, s[22:23]
	s_cmp_eq_u64 s[0:1], 0
	s_cbranch_scc1 .Lp11_g1_a2
	global_load_dwordx4 v[100:103], v166, s[22:23]
; template <int DQK>
; __device__ __forceinline__ void attn_unit64(LAS char* lds, const bf16x8 (&qa)[DQK / 16], const bf16x8 (&qb)[DQK / 16],
;                                             const bf16_t* Kg, int ldk, const bf16_t* Vg, int ldv, int t0, int t1, bf16_t* Oga, int ogb_off) {
;     ...
;         for (int kv = 0; kv < 2; ++kv) {
;             __builtin_amdgcn_iglp_opt(0);
;             f32x16 sa, sb;
; #pragma unroll
;             for (int i = 0; i < 16; ++i) { sa[i] = 0.f; sb[i] = 0.f; }
; #pragma unroll
;             for (int ds = 0; ds < DQK / 16; ++ds) {
;                 const bf16x8 kf = *(const LAS bf16x8*)(kb + kv * 32 * KP + ds * 32);
;                 sa = __builtin_amdgcn_mfma_f32_32x32x16_bf16(kf, qa[ds], sa, 0, 0, 0);
;                 sb = __builtin_amdgcn_mfma_f32_32x32x16_bf16(kf, qb[ds], sb, 0, 0, 0);
;             }
; #pragma unroll
;             for (int i = 0; i < 16; i += 2) { sa[i] = __builtin_amdgcn_exp2f(sa[i]); sa[i + 1] = __builtin_amdgcn_exp2f(sa[i + 1]); la0 += sa[i]; la1 += sa[i + 1];
;                                                sb[i] = __builtin_amdgcn_exp2f(sb[i]); sb[i + 1] = __builtin_amdgcn_exp2f(sb[i + 1]); lb0 += sb[i]; lb1 += sb[i + 1]; }
;             bf16x8 pa[2], pb[2]; pa[0] = pack8(sa, 0); pa[1] = pack8(sa, 1); pb[0] = pack8(sb, 0); pb[1] = pack8(sb, 1);
; #pragma unroll
;             for (int s2 = 0; s2 < 2; ++s2) {
;                 const int s = 2 * kv + s2;
;                 const s16x4 a0 = vtr(vb + (16 * s) * 64), a1 = vtr(vb + (16 * s + 8) * 64), c0 = vtr(vb + 4096 + (16 * s) * 64), c1 = vtr(vb + 4096 + (16 * s + 8) * 64);
;                 const bf16x8 va = (bf16x8){a0[0], a0[1], a0[2], a0[3], a1[0], a1[1], a1[2], a1[3]}, vc = (bf16x8){c0[0], c0[1], c0[2], c0[3], c1[0], c1[1], c1[2], c1[3]};
;                 oa0 = __builtin_amdgcn_mfma_f32_32x32x16_bf16(va, pa[s2], oa0, 0, 0, 0);
;                 oa1 = __builtin_amdgcn_mfma_f32_32x32x16_bf16(vc, pa[s2], oa1, 0, 0, 0);
;                 ob0 = __builtin_amdgcn_mfma_f32_32x32x16_bf16(va, pb[s2], ob0, 0, 0, 0);
;                 ob1 = __builtin_amdgcn_mfma_f32_32x32x16_bf16(vc, pb[s2], ob1, 0, 0, 0);
;             }
;         }
;         if (more) { const unsigned bo = (cur ^ 1) * BUF; *(LAS u32x4*)(lds + bo + kdst0) = kreg0; if (k2) *(LAS u32x4*)(lds + bo + kdst1) = kreg1; *(LAS u32x4*)(lds + bo + vdst) = vreg; }
;         __syncthreads();
.Lp11_g1_a2:
	global_load_dwordx4 v[104:107], v[180:181], off
	s_waitcnt lgkmcnt(2)
	v_mfma_f32_32x32x16_bf16 v[80:95], v[182:185], v[128:131], 0
	v_exp_f32_e32 v64, v64
	v_exp_f32_e32 v65, v65
	v_exp_f32_e32 v66, v66
	v_exp_f32_e32 v67, v67
	v_mfma_f32_32x32x16_bf16 v[80:95], v[186:189], v[124:127], v[80:95]
	v_exp_f32_e32 v68, v68
	v_exp_f32_e32 v69, v69
	v_cvt_pk_bf16_f32 v230, v64, v65
	v_cvt_pk_bf16_f32 v231, v66, v67
	v_mfma_f32_32x32x16_bf16 v[80:95], v[190:193], v[120:123], v[80:95]
	v_exp_f32_e32 v70, v70
	v_exp_f32_e32 v71, v71
	v_exp_f32_e32 v72, v72
	v_cvt_pk_bf16_f32 v232, v68, v69
	v_mfma_f32_32x32x16_bf16 v[80:95], v[194:197], v[116:119], v[80:95]
	v_exp_f32_e32 v73, v73
	v_exp_f32_e32 v74, v74
	v_cvt_pk_bf16_f32 v233, v70, v71
	v_exp_f32_e32 v75, v75
	v_mfma_f32_32x32x16_bf16 v[80:95], v[198:201], v[108:111], v[80:95]
	v_exp_f32_e32 v76, v76
	v_exp_f32_e32 v77, v77
	v_cvt_pk_bf16_f32 v234, v72, v73
	v_cvt_pk_bf16_f32 v235, v74, v75
	v_mfma_f32_32x32x16_bf16 v[80:95], v[202:205], v[112:115], v[80:95]
	v_exp_f32_e32 v78, v78
	v_exp_f32_e32 v79, v79
	v_cvt_pk_bf16_f32 v236, v76, v77
	v_cvt_pk_bf16_f32 v237, v78, v79
	v_mfma_f32_32x32x16_bf16 v[16:31], v[248:251], v[230:233], v[16:31]
	ds_read_b64_tr_b16 v[248:249], v239 offset:58368
	ds_read_b64_tr_b16 v[250:251], v239 offset:58880
	v_add_f32_e32 v172, v172, v64
	v_add_f32_e32 v173, v173, v65
	v_add_f32_e32 v172, v172, v66
	v_add_f32_e32 v173, v173, v67
	v_mfma_f32_32x32x16_bf16 v[0:15], v[252:255], v[230:233], v[0:15]
	ds_read_b64_tr_b16 v[252:253], v239 offset:62464
	ds_read_b64_tr_b16 v[254:255], v239 offset:62976
	v_add_f32_e32 v172, v172, v68
	v_add_f32_e32 v173, v173, v69
	v_add_f32_e32 v172, v172, v70
	v_add_f32_e32 v173, v173, v71
	v_mfma_f32_32x32x16_bf16 v[16:31], v[214:217], v[234:237], v[16:31]
	ds_read_b64_tr_b16 v[214:215], v239 offset:59392
	ds_read_b64_tr_b16 v[216:217], v239 offset:59904
	v_add_f32_e32 v172, v172, v72
	v_add_f32_e32 v173, v173, v73
	v_add_f32_e32 v172, v172, v74
	v_add_f32_e32 v173, v173, v75
	v_mfma_f32_32x32x16_bf16 v[0:15], v[218:221], v[234:237], v[0:15]
	ds_read_b64_tr_b16 v[218:219], v239 offset:63488
	ds_read_b64_tr_b16 v[220:221], v239 offset:64000
	v_add_f32_e32 v172, v172, v76
	v_add_f32_e32 v173, v173, v77
	v_add_f32_e32 v172, v172, v78
	v_add_f32_e32 v173, v173, v79
	s_waitcnt lgkmcnt(8)
	s_barrier
	v_mfma_f32_32x32x16_bf16 v[64:79], v[182:185], v[132:135], 0
	ds_read_b128 v[182:185], v238
	v_exp_f32_e32 v80, v80
	v_exp_f32_e32 v81, v81
	v_exp_f32_e32 v82, v82
	v_exp_f32_e32 v83, v83
	v_mfma_f32_32x32x16_bf16 v[64:79], v[186:189], v[136:139], v[64:79]
	ds_read_b128 v[186:189], v238 offset:32
	v_exp_f32_e32 v84, v84
	v_exp_f32_e32 v85, v85
	v_cvt_pk_bf16_f32 v222, v80, v81
	v_cvt_pk_bf16_f32 v223, v82, v83
	v_mfma_f32_32x32x16_bf16 v[64:79], v[190:193], v[140:143], v[64:79]
	ds_read_b128 v[190:193], v238 offset:64
	v_exp_f32_e32 v86, v86
	v_exp_f32_e32 v87, v87
	v_exp_f32_e32 v88, v88
	v_cvt_pk_bf16_f32 v224, v84, v85
	v_mfma_f32_32x32x16_bf16 v[64:79], v[194:197], v[144:147], v[64:79]
	ds_read_b128 v[194:197], v238 offset:96
	v_exp_f32_e32 v89, v89
	v_exp_f32_e32 v90, v90
	v_cvt_pk_bf16_f32 v225, v86, v87
	v_exp_f32_e32 v91, v91
	v_mfma_f32_32x32x16_bf16 v[64:79], v[198:201], v[148:151], v[64:79]
	ds_read_b128 v[198:201], v238 offset:128
	v_exp_f32_e32 v92, v92
	v_exp_f32_e32 v93, v93
	v_cvt_pk_bf16_f32 v226, v88, v89
	v_cvt_pk_bf16_f32 v227, v90, v91
	v_mfma_f32_32x32x16_bf16 v[64:79], v[202:205], v[152:155], v[64:79]
	ds_read_b128 v[202:205], v238 offset:160
	v_exp_f32_e32 v94, v94
	v_exp_f32_e32 v95, v95
	v_cvt_pk_bf16_f32 v228, v92, v93
	v_cvt_pk_bf16_f32 v229, v94, v95
	s_waitcnt lgkmcnt(6)
	v_mfma_f32_32x32x16_bf16 v[32:47], v[248:251], v[222:225], v[32:47]
	v_add_f32_e32 v170, v170, v80
	v_add_f32_e32 v171, v171, v81
	v_add_f32_e32 v170, v170, v82
	v_add_f32_e32 v171, v171, v83
	v_mfma_f32_32x32x16_bf16 v[48:63], v[252:255], v[222:225], v[48:63]
	v_add_f32_e32 v170, v170, v84
	v_add_f32_e32 v171, v171, v85
	v_add_f32_e32 v170, v170, v86
	v_add_f32_e32 v171, v171, v87
	v_mfma_f32_32x32x16_bf16 v[32:47], v[214:217], v[226:229], v[32:47]
	v_add_f32_e32 v170, v170, v88
	v_add_f32_e32 v171, v171, v89
	v_add_f32_e32 v170, v170, v90
	v_add_f32_e32 v171, v171, v91
	v_mfma_f32_32x32x16_bf16 v[48:63], v[218:221], v[226:229], v[48:63]
	v_add_f32_e32 v170, v170, v92
	v_add_f32_e32 v171, v171, v93
	v_add_f32_e32 v170, v170, v94
	v_add_f32_e32 v171, v171, v95
	s_add_i32 s4, s4, 1
	s_cmp_lt_u32 s4, s39
	s_cbranch_scc1 .Lp11_loop
.Lp11_drain:
	v_exp_f32_e32 v64, v64
	v_exp_f32_e32 v65, v65
	v_exp_f32_e32 v66, v66
	v_exp_f32_e32 v67, v67
	v_exp_f32_e32 v68, v68
	v_exp_f32_e32 v69, v69
	v_cvt_pk_bf16_f32 v230, v64, v65
	v_cvt_pk_bf16_f32 v231, v66, v67
	v_exp_f32_e32 v70, v70
	v_exp_f32_e32 v71, v71
	v_exp_f32_e32 v72, v72
	v_cvt_pk_bf16_f32 v232, v68, v69
	v_exp_f32_e32 v73, v73
	v_exp_f32_e32 v74, v74
	v_cvt_pk_bf16_f32 v233, v70, v71
	v_exp_f32_e32 v75, v75
	v_exp_f32_e32 v76, v76
	v_exp_f32_e32 v77, v77
	v_cvt_pk_bf16_f32 v234, v72, v73
	v_cvt_pk_bf16_f32 v235, v74, v75
	v_exp_f32_e32 v78, v78
	v_exp_f32_e32 v79, v79
	v_cvt_pk_bf16_f32 v236, v76, v77
	v_cvt_pk_bf16_f32 v237, v78, v79
	v_add_f32_e32 v172, v172, v64
	v_add_f32_e32 v173, v173, v65
	v_add_f32_e32 v172, v172, v66
	v_add_f32_e32 v173, v173, v67
	v_add_f32_e32 v172, v172, v68
	v_add_f32_e32 v173, v173, v69
	v_add_f32_e32 v172, v172, v70
	v_add_f32_e32 v173, v173, v71
	v_add_f32_e32 v172, v172, v72
	v_add_f32_e32 v173, v173, v73
	v_add_f32_e32 v172, v172, v74
	v_add_f32_e32 v173, v173, v75
	v_add_f32_e32 v172, v172, v76
	v_add_f32_e32 v173, v173, v77
	v_add_f32_e32 v172, v172, v78
	v_add_f32_e32 v173, v173, v79
	s_nop 1
	v_mfma_f32_32x32x16_bf16 v[16:31], v[248:251], v[230:233], v[16:31]
	v_mfma_f32_32x32x16_bf16 v[0:15], v[252:255], v[230:233], v[0:15]
	v_mfma_f32_32x32x16_bf16 v[16:31], v[214:217], v[234:237], v[16:31]
	v_mfma_f32_32x32x16_bf16 v[0:15], v[218:221], v[234:237], v[0:15]
	s_waitcnt vmcnt(0)
	s_waitcnt lgkmcnt(0)
	s_barrier
	s_branch .LBB0_1115

; #define LAS __attribute__((address_space(3)))
; __global__ void __launch_bounds__(512) fwd_megakernel(Args args) {
;     extern __shared__ __attribute__((aligned(16))) unsigned char lds_raw[];
;     cg::grid_group grid = cg::this_grid();
;     LAS unsigned char* lds = (LAS unsigned char*)lds_raw;
	.amdhsa_kernel _Z14fwd_megakernel4Args
		.amdhsa_group_segment_fixed_size 0
		.amdhsa_private_segment_fixed_size 0
		.amdhsa_kernarg_size 456
		.amdhsa_user_sgpr_count 2
		.amdhsa_user_sgpr_dispatch_ptr 0
		.amdhsa_user_sgpr_queue_ptr 0
		.amdhsa_user_sgpr_kernarg_segment_ptr 1
		.amdhsa_user_sgpr_dispatch_id 0
		.amdhsa_user_sgpr_kernarg_preload_length 0
		.amdhsa_user_sgpr_kernarg_preload_offset 0
		.amdhsa_user_sgpr_private_segment_size 0
		.amdhsa_uses_dynamic_stack 0
		.amdhsa_enable_private_segment 0
		.amdhsa_system_sgpr_workgroup_id_x 1
		.amdhsa_system_sgpr_workgroup_id_y 0
		.amdhsa_system_sgpr_workgroup_id_z 0
		.amdhsa_system_sgpr_workgroup_info 0
		.amdhsa_system_vgpr_workitem_id 2
		.amdhsa_next_free_vgpr 256
		.amdhsa_next_free_sgpr 98
		.amdhsa_accum_offset 256
		.amdhsa_reserve_vcc 1
		.amdhsa_float_round_mode_32 0
		.amdhsa_float_round_mode_16_64 0
		.amdhsa_float_denorm_mode_32 3
		.amdhsa_float_denorm_mode_16_64 3
		.amdhsa_dx10_clamp 1
		.amdhsa_ieee_mode 1
		.amdhsa_fp16_overflow 0
		.amdhsa_tg_split 0
		.amdhsa_exception_fp_ieee_invalid_op 0
		.amdhsa_exception_fp_denorm_src 0
		.amdhsa_exception_fp_ieee_div_zero 0
		.amdhsa_exception_fp_ieee_overflow 0
		.amdhsa_exception_fp_ieee_underflow 0
		.amdhsa_exception_fp_ieee_inexact 0
		.amdhsa_exception_int_div_zero 0
	.end_amdhsa_kernel

; #define LAS __attribute__((address_space(3)))
; __global__ void __launch_bounds__(512) fwd_megakernel(Args args) {
;     extern __shared__ __attribute__((aligned(16))) unsigned char lds_raw[];
;     cg::grid_group grid = cg::this_grid();
;     LAS unsigned char* lds = (LAS unsigned char*)lds_raw;
amdhsa.kernels:
  - .agpr_count:     0
    .args:
      - .offset:         0
        .size:           200
        .value_kind:     by_value
      - .offset:         200
        .size:           4
        .value_kind:     hidden_block_count_x
      - .offset:         204
        .size:           4
        .value_kind:     hidden_block_count_y
      - .offset:         208
        .size:           4
        .value_kind:     hidden_block_count_z
      - .offset:         212
        .size:           2
        .value_kind:     hidden_group_size_x
      - .offset:         214
        .size:           2
        .value_kind:     hidden_group_size_y
      - .offset:         216
        .size:           2
        .value_kind:     hidden_group_size_z
      - .offset:         218
        .size:           2
        .value_kind:     hidden_remainder_x
      - .offset:         220
        .size:           2
        .value_kind:     hidden_remainder_y
      - .offset:         222
        .size:           2
        .value_kind:     hidden_remainder_z
      - .offset:         240
        .size:           8
        .value_kind:     hidden_global_offset_x
      - .offset:         248
        .size:           8
        .value_kind:     hidden_global_offset_y
      - .offset:         256
        .size:           8
        .value_kind:     hidden_global_offset_z
      - .offset:         264
        .size:           2
        .value_kind:     hidden_grid_dims
      - .offset:         288
        .size:           8
        .value_kind:     hidden_multigrid_sync_arg
      - .offset:         320
        .size:           4
        .value_kind:     hidden_dynamic_lds_size
    .group_segment_fixed_size: 0
    .kernarg_segment_align: 8
    .kernarg_segment_size: 456
    .language:       OpenCL C
    .language_version:
      - 2
      - 0
    .max_flat_workgroup_size: 512
    .name:           _Z14fwd_megakernel4Args
    .private_segment_fixed_size: 0
    .sgpr_count:     104
    .sgpr_spill_count: 90
    .symbol:         _Z14fwd_megakernel4Args.kd
    .uniform_work_group_size: 1
    .uses_dynamic_stack: false
    .vgpr_count:     256
    .vgpr_spill_count: 0
    .wavefront_size: 64
